# flash loops: tree max, cross-half max exchange only on the rescale path, scalar M0 arithmetic for DMA pieces
# speedup vs baseline: 1.0491x; 1.0131x over previous
; template <int DQK, int DV, int NKH, int MODE>
; DEV void flash_unit(const FlashArgs& fa, char* smem, f32x16 (&oacc)[DV / 32], float& linv_out) {
;     ...
;       const char* sb = smem + (it & (NSTG - 1)) * STAGE;
;       const char* kb = sb + kh * 8192 + r * 128;
;       const char* kb32 = sb + OFF_K32 + r * 64;
;       const char* vb = sb + OFF_V;
;       f32x16 st[2];
;       bf16x8 kfr[2][NS];
; #pragma unroll
;       for (int k2 = 0; k2 < 2; ++k2)
; #pragma unroll
;         for (int s = 0; s < NS; ++s) {
;           if (s < 4) kfr[k2][s] = *(const bf16x8*)(kb + k2 * 32 * 128 + kxo[s]);
;           else kfr[k2][s] = *(const bf16x8*)(kb32 + k2 * 32 * 64 + (((2 * (s - 4) + h) ^ k32x) << 4));
;         }
;       __builtin_amdgcn_sched_barrier(0);
; #pragma unroll
;       for (int k2 = 0; k2 < 2; ++k2) {
; #pragma unroll
;         for (int s = 0; s < NS; ++s) {
;           const bf16x8 kf = kfr[k2][s];
;           if (s == 0) st[k2] = MFMA(kf, qf[s], negm);
;           else st[k2] = MFMA(kf, qf[s], st[k2]);
;           constexpr int NQK = 2 * NS, EVERY = NQK / LPT;
;           const int m = k2 * NS + s;
;           if ((m + 1) % EVERY == 0 && (m + 1) / EVERY <= LPT) {
;             __builtin_amdgcn_sched_barrier(0);
;             if (pre) issue_piece(it + 3, (m + 1) / EVERY - 1);
;             __builtin_amdgcn_sched_barrier(0);
;           }
;         }
;       }
;       if (MODE == 1 && it >= 4) {
;         const int dr = krow - na_row + 7;
;         const float* bp = rpbs + dr * 31;
; #pragma unroll
;         for (int k2 = 0; k2 < 2; ++k2)
; #pragma unroll
;           for (int e = 0; e < 16; ++e) {
;             const int kc = k2 * 32 + crow_of(e, h);
;             const bool valid = (kc >= na_cstart) && (kc < na_cstart + 16);
;             const int idx = min(max(kc - na_qc + 15, 0), 30);
;             const float bv = bp[idx];
;             st[k2][e] = valid ? st[k2][e] + bv : -1e30f;
;           }
;       }
;       float rel = st[0][0];
; #pragma unroll
;       for (int e = 1; e < 16; ++e) rel = fmaxf(rel, st[0][e]);
; #pragma unroll
;       for (int e = 0; e < 16; ++e) rel = fmaxf(rel, st[1][e]);
;       rel = half_max(rel);
;       const bool first = (it == 0);
;       if (first || __builtin_amdgcn_ballot_w64(rel > 8.f) != 0) {
;         const float d = first ? rel : fmaxf(rel, 0.f);
;         const float alpha = fast_exp2(-d);
;         mrun += d;
.LBB0_80:
	s_add_i32 s15, s17, 0x8000
	s_and_b32 s0, s15, 0x18000
	s_add_i32 s16, s0, 0
	v_add3_u32 v80, s16, v192, v193
	v_add_u32_e32 v81, v80, v184
	v_add_u32_e32 v82, v80, v185
	v_add_u32_e32 v84, v80, v186
	s_barrier
	v_add_u32_e32 v96, v80, v187
	ds_read_b128 v[88:91], v81
	ds_read_b128 v[136:139], v81 offset:4096
	ds_read_b128 v[92:95], v82
	ds_read_b128 v[140:143], v82 offset:4096
	ds_read_b128 v[80:83], v84
	ds_read_b128 v[128:131], v84 offset:4096
	ds_read_b128 v[84:87], v96
	ds_read_b128 v[132:135], v96 offset:4096
	s_add_i32 s0, s17, 0x20000
	s_and_b32 s0, s0, 0x18000
	v_add_u32_e32 v144, s0, v183
	s_waitcnt lgkmcnt(7)
	v_mfma_f32_32x32x16_bf16 v[96:111], v[88:91], v[120:123], v[64:79]
	s_waitcnt lgkmcnt(5)
	v_mfma_f32_32x32x16_bf16 v[96:111], v[92:95], v[112:115], v[96:111]
	v_readfirstlane_b32 s1, v144
	s_cmp_ge_u32 s4, s11
	s_cbranch_scc1 .Ldf_d1
	s_mov_b32 m0, s1
	s_nop 0
	global_load_lds_dwordx4 v[164:165], off
.Ldf_d1:
	s_waitcnt lgkmcnt(3)
	v_mfma_f32_32x32x16_bf16 v[96:111], v[80:83], v[116:119], v[96:111]
	s_waitcnt lgkmcnt(1)
	v_mfma_f32_32x32x16_bf16 v[96:111], v[84:87], v[124:127], v[96:111]
	s_cmp_ge_u32 s4, s11
	s_cbranch_scc1 .Ldf_d2
	s_add_i32 m0, s1, 0x2000
	s_nop 0
	global_load_lds_dwordx4 v[162:163], off
.Ldf_d2:
	v_mfma_f32_32x32x16_bf16 v[80:95], v[136:139], v[120:123], v[64:79]
	v_mfma_f32_32x32x16_bf16 v[80:95], v[140:143], v[112:115], v[80:95]
	s_cmp_ge_u32 s4, s11
	s_cbranch_scc1 .Ldf_d3
	s_add_i32 m0, s1, 0x4000
	s_nop 0
	global_load_lds_dwordx4 v[160:161], off
.Ldf_d3:
	v_mfma_f32_32x32x16_bf16 v[80:95], v[128:131], v[116:119], v[80:95]
	s_waitcnt lgkmcnt(0)
	v_mfma_f32_32x32x16_bf16 v[80:95], v[132:135], v[124:127], v[80:95]
	s_cmp_ge_u32 s4, s11
	s_cbranch_scc1 .LBB0_88
	s_add_i32 m0, s1, 0x6000
	s_nop 0
	global_load_lds_dwordx4 v[158:159], off
.LBB0_88:
	v_add3_u32 v251, v194, v195, v196
	v_add3_u32 v252, v194, v197, v196
	v_add3_u32 v243, s16, v188, v251
	v_add3_u32 v244, s16, v188, v252
	v_add3_u32 v245, s16, v189, v251
	v_add3_u32 v246, s16, v189, v252
	v_add3_u32 v247, s16, v190, v251
	v_add3_u32 v248, s16, v190, v252
	v_add3_u32 v249, s16, v191, v251
	v_add3_u32 v250, s16, v191, v252
	ds_read_b64_tr_b16 v[128:129], v243 offset:16384
	ds_read_b64_tr_b16 v[130:131], v244 offset:18432
	ds_read_b64_tr_b16 v[132:133], v245 offset:16384
	ds_read_b64_tr_b16 v[134:135], v246 offset:18432
	ds_read_b64_tr_b16 v[136:137], v247 offset:16384
	ds_read_b64_tr_b16 v[138:139], v248 offset:18432
	ds_read_b64_tr_b16 v[140:141], v249 offset:16384
	ds_read_b64_tr_b16 v[142:143], v250 offset:18432
	v_max3_f32 v252, v96, v97, v98
	v_max3_f32 v251, v99, v100, v101
	v_max3_f32 v254, v102, v103, v104
	v_max3_f32 v144, v105, v106, v107
	v_max3_f32 v252, v252, v108, v109
	v_max3_f32 v251, v251, v110, v111
	v_max3_f32 v254, v254, v80, v81
	v_max3_f32 v144, v144, v82, v83
	v_max3_f32 v252, v252, v84, v85
	v_max3_f32 v251, v251, v86, v87
	v_max3_f32 v254, v254, v88, v89
	v_max3_f32 v144, v144, v90, v91
	v_max3_f32 v252, v252, v92, v93
	v_max3_f32 v251, v251, v94, v95
	v_max3_f32 v252, v252, v251, v254
	v_max_f32_e32 v252, v252, v144
	v_cmp_lt_f32_e32 vcc, s33, v252
	s_cbranch_vccz .LBB0_90
	v_mov_b32_e32 v251, v252
	s_nop 1
	v_permlane32_swap_b32_e32 v252, v251
	v_max_f32_e32 v252, v252, v251
	v_max_f32_e32 v64, 0, v252
	v_exp_f32_e64 v66, -v64
	v_add_f32_e32 v157, v157, v64
	v_pk_add_f32 v[96:97], v[96:97], v[64:65] op_sel_hi:[1,0] neg_lo:[0,1] neg_hi:[0,1]
	v_pk_add_f32 v[98:99], v[98:99], v[64:65] op_sel_hi:[1,0] neg_lo:[0,1] neg_hi:[0,1]
	v_pk_add_f32 v[100:101], v[100:101], v[64:65] op_sel_hi:[1,0] neg_lo:[0,1] neg_hi:[0,1]
	v_pk_add_f32 v[102:103], v[102:103], v[64:65] op_sel_hi:[1,0] neg_lo:[0,1] neg_hi:[0,1]
	v_pk_add_f32 v[104:105], v[104:105], v[64:65] op_sel_hi:[1,0] neg_lo:[0,1] neg_hi:[0,1]
	v_pk_add_f32 v[106:107], v[106:107], v[64:65] op_sel_hi:[1,0] neg_lo:[0,1] neg_hi:[0,1]
	v_pk_add_f32 v[108:109], v[108:109], v[64:65] op_sel_hi:[1,0] neg_lo:[0,1] neg_hi:[0,1]
	v_pk_add_f32 v[110:111], v[110:111], v[64:65] op_sel_hi:[1,0] neg_lo:[0,1] neg_hi:[0,1]
	v_pk_add_f32 v[80:81], v[80:81], v[64:65] op_sel_hi:[1,0] neg_lo:[0,1] neg_hi:[0,1]
	v_pk_add_f32 v[82:83], v[82:83], v[64:65] op_sel_hi:[1,0] neg_lo:[0,1] neg_hi:[0,1]
	v_pk_add_f32 v[84:85], v[84:85], v[64:65] op_sel_hi:[1,0] neg_lo:[0,1] neg_hi:[0,1]
	v_pk_add_f32 v[86:87], v[86:87], v[64:65] op_sel_hi:[1,0] neg_lo:[0,1] neg_hi:[0,1]
	v_pk_add_f32 v[88:89], v[88:89], v[64:65] op_sel_hi:[1,0] neg_lo:[0,1] neg_hi:[0,1]
	v_pk_add_f32 v[90:91], v[90:91], v[64:65] op_sel_hi:[1,0] neg_lo:[0,1] neg_hi:[0,1]
	v_pk_add_f32 v[92:93], v[92:93], v[64:65] op_sel_hi:[1,0] neg_lo:[0,1] neg_hi:[0,1]
	v_pk_add_f32 v[94:95], v[94:95], v[64:65] op_sel_hi:[1,0] neg_lo:[0,1] neg_hi:[0,1]
	v_xor_b32_e32 v64, 0x80000000, v157
	v_pk_mul_f32 v[46:47], v[46:47], v[66:67] op_sel_hi:[1,0]
	v_pk_mul_f32 v[44:45], v[44:45], v[66:67] op_sel_hi:[1,0]
	v_pk_mul_f32 v[42:43], v[42:43], v[66:67] op_sel_hi:[1,0]
	v_pk_mul_f32 v[40:41], v[40:41], v[66:67] op_sel_hi:[1,0]
	v_pk_mul_f32 v[38:39], v[38:39], v[66:67] op_sel_hi:[1,0]
	v_pk_mul_f32 v[36:37], v[36:37], v[66:67] op_sel_hi:[1,0]
	v_pk_mul_f32 v[34:35], v[34:35], v[66:67] op_sel_hi:[1,0]
	v_pk_mul_f32 v[32:33], v[32:33], v[66:67] op_sel_hi:[1,0]
	v_pk_mul_f32 v[62:63], v[62:63], v[66:67] op_sel_hi:[1,0]
	v_pk_mul_f32 v[60:61], v[60:61], v[66:67] op_sel_hi:[1,0]
	v_pk_mul_f32 v[58:59], v[58:59], v[66:67] op_sel_hi:[1,0]
	v_pk_mul_f32 v[56:57], v[56:57], v[66:67] op_sel_hi:[1,0]
	v_pk_mul_f32 v[54:55], v[54:55], v[66:67] op_sel_hi:[1,0]
	v_pk_mul_f32 v[52:53], v[52:53], v[66:67] op_sel_hi:[1,0]
	v_pk_mul_f32 v[50:51], v[50:51], v[66:67] op_sel_hi:[1,0]
	v_pk_mul_f32 v[48:49], v[48:49], v[66:67] op_sel_hi:[1,0]
	v_pk_mul_f32 v[30:31], v[30:31], v[66:67] op_sel_hi:[1,0]
	v_pk_mul_f32 v[28:29], v[28:29], v[66:67] op_sel_hi:[1,0]
	v_pk_mul_f32 v[26:27], v[26:27], v[66:67] op_sel_hi:[1,0]
	v_pk_mul_f32 v[24:25], v[24:25], v[66:67] op_sel_hi:[1,0]
	v_pk_mul_f32 v[22:23], v[22:23], v[66:67] op_sel_hi:[1,0]
	v_pk_mul_f32 v[20:21], v[20:21], v[66:67] op_sel_hi:[1,0]
	v_pk_mul_f32 v[18:19], v[18:19], v[66:67] op_sel_hi:[1,0]
	v_pk_mul_f32 v[16:17], v[16:17], v[66:67] op_sel_hi:[1,0]
	v_pk_mul_f32 v[14:15], v[14:15], v[66:67] op_sel_hi:[1,0]
	v_pk_mul_f32 v[12:13], v[12:13], v[66:67] op_sel_hi:[1,0]
	v_pk_mul_f32 v[10:11], v[10:11], v[66:67] op_sel_hi:[1,0]
	v_pk_mul_f32 v[8:9], v[8:9], v[66:67] op_sel_hi:[1,0]
	v_pk_mul_f32 v[6:7], v[6:7], v[66:67] op_sel_hi:[1,0]
	v_pk_mul_f32 v[4:5], v[4:5], v[66:67] op_sel_hi:[1,0]
	v_pk_mul_f32 v[2:3], v[2:3], v[66:67] op_sel_hi:[1,0]
	v_pk_mul_f32 v[0:1], v[0:1], v[66:67] op_sel_hi:[1,0]
	v_mul_f32_e32 v156, v156, v66
	v_mov_b32_e32 v65, v64
	v_mov_b32_e32 v66, v64
	v_mov_b32_e32 v67, v64
	v_mov_b32_e32 v68, v64
	v_mov_b32_e32 v69, v64
	v_mov_b32_e32 v70, v64
	v_mov_b32_e32 v71, v64
	v_mov_b32_e32 v72, v64
	v_mov_b32_e32 v73, v64
	v_mov_b32_e32 v74, v64
	v_mov_b32_e32 v75, v64
	v_mov_b32_e32 v76, v64
	v_mov_b32_e32 v77, v64
	v_mov_b32_e32 v78, v64
	v_mov_b32_e32 v79, v64

; template <int DQK, int DV, int NKH, int MODE>
; DEV void flash_unit(const FlashArgs& fa, char* smem, f32x16 (&oacc)[DV / 32], float& linv_out) {
;     ...
;       const char* sb = smem + (it & (NSTG - 1)) * STAGE;
;       const char* kb = sb + kh * 8192 + r * 128;
;       const char* kb32 = sb + OFF_K32 + r * 64;
;       const char* vb = sb + OFF_V;
;       f32x16 st[2];
;       bf16x8 kfr[2][NS];
; #pragma unroll
;       for (int k2 = 0; k2 < 2; ++k2)
; #pragma unroll
;         for (int s = 0; s < NS; ++s) {
;           if (s < 4) kfr[k2][s] = *(const bf16x8*)(kb + k2 * 32 * 128 + kxo[s]);
;           else kfr[k2][s] = *(const bf16x8*)(kb32 + k2 * 32 * 64 + (((2 * (s - 4) + h) ^ k32x) << 4));
;         }
;       __builtin_amdgcn_sched_barrier(0);
; #pragma unroll
;       for (int k2 = 0; k2 < 2; ++k2) {
; #pragma unroll
;         for (int s = 0; s < NS; ++s) {
;           const bf16x8 kf = kfr[k2][s];
;           if (s == 0) st[k2] = MFMA(kf, qf[s], negm);
;           else st[k2] = MFMA(kf, qf[s], st[k2]);
;           constexpr int NQK = 2 * NS, EVERY = NQK / LPT;
;           const int m = k2 * NS + s;
;           if ((m + 1) % EVERY == 0 && (m + 1) / EVERY <= LPT) {
;             __builtin_amdgcn_sched_barrier(0);
;             if (pre) issue_piece(it + 3, (m + 1) / EVERY - 1);
;             __builtin_amdgcn_sched_barrier(0);
;           }
;         }
;       }
;       if (MODE == 1 && it >= 4) {
;         const int dr = krow - na_row + 7;
;         const float* bp = rpbs + dr * 31;
; #pragma unroll
;         for (int k2 = 0; k2 < 2; ++k2)
; #pragma unroll
;           for (int e = 0; e < 16; ++e) {
;             const int kc = k2 * 32 + crow_of(e, h);
;             const bool valid = (kc >= na_cstart) && (kc < na_cstart + 16);
;             const int idx = min(max(kc - na_qc + 15, 0), 30);
;             const float bv = bp[idx];
;             st[k2][e] = valid ? st[k2][e] + bv : -1e30f;
;           }
;       }
;       float rel = st[0][0];
; #pragma unroll
;       for (int e = 1; e < 16; ++e) rel = fmaxf(rel, st[0][e]);
; #pragma unroll
;       for (int e = 0; e < 16; ++e) rel = fmaxf(rel, st[1][e]);
;       rel = half_max(rel);
;       const bool first = (it == 0);
;       if (first || __builtin_amdgcn_ballot_w64(rel > 8.f) != 0) {
;         const float d = first ? rel : fmaxf(rel, 0.f);
;         const float alpha = fast_exp2(-d);
;         mrun += d;
.Lmla_waitd:
	s_add_i32 s2, s19, -3
	s_and_b32 s2, s2, 3
	s_mulk_i32 s2, 0x5000
	s_add_i32 s6, s2, 0
	v_add_u32_e32 v48, s6, v146
	v_add_u32_e32 v49, s6, v148
	v_add_u32_e32 v50, v48, v151
	v_add_u32_e32 v51, v48, v152
	v_add_u32_e32 v52, v48, v153
	v_add_u32_e32 v48, v48, v154
	v_add_u32_e32 v53, v49, v149
	s_barrier
	v_add_u32_e32 v64, v49, v150
	ds_read_b128 v[56:59], v50
	ds_read_b128 v[120:123], v50 offset:4096
	ds_read_b128 v[60:63], v51
	ds_read_b128 v[124:127], v51 offset:4096
	ds_read_b128 v[160:163], v52
	ds_read_b128 v[104:107], v52 offset:4096
	ds_read_b128 v[182:185], v48
	ds_read_b128 v[108:111], v48 offset:4096
	ds_read_b128 v[48:51], v53 offset:8192
	ds_read_b128 v[112:115], v53 offset:10240
	ds_read_b128 v[52:55], v64 offset:8192
	ds_read_b128 v[116:119], v64 offset:10240
	s_and_b32 s7, s19, 3
	s_mulk_i32 s7, 0x5000
	v_add_u32_e32 v144, s7, v143
	s_waitcnt lgkmcnt(11)
	v_mfma_f32_32x32x16_bf16 v[64:79], v[56:59], v[80:83], v[32:47]
	s_waitcnt lgkmcnt(9)
	v_mfma_f32_32x32x16_bf16 v[64:79], v[60:63], v[84:87], v[64:79]
	v_readfirstlane_b32 s7, v144
	s_waitcnt lgkmcnt(7)
	v_mfma_f32_32x32x16_bf16 v[64:79], v[160:163], v[88:91], v[64:79]
	s_waitcnt lgkmcnt(5)
	v_mfma_f32_32x32x16_bf16 v[64:79], v[182:185], v[92:95], v[64:79]
	s_cmp_ge_u32 s19, s18
	s_cbranch_scc1 .Lmla_d1
	s_mov_b32 m0, s7
	s_nop 0
	global_load_lds_dwordx4 v[140:141], off
.Lmla_d1:
	s_waitcnt lgkmcnt(0)
	v_mfma_f32_32x32x16_bf16 v[64:79], v[48:51], v[96:99], v[64:79]
	v_mfma_f32_32x32x16_bf16 v[64:79], v[52:55], v[100:103], v[64:79]
	v_mfma_f32_32x32x16_bf16 v[48:63], v[120:123], v[80:83], v[32:47]
	v_mfma_f32_32x32x16_bf16 v[48:63], v[124:127], v[84:87], v[48:63]
	s_cmp_ge_u32 s19, s18
	s_cbranch_scc1 .Lmla_d2
	s_add_i32 m0, s7, 0x2000
	s_nop 0
	global_load_lds_dwordx4 v[138:139], off
.Lmla_d2:
	v_mfma_f32_32x32x16_bf16 v[48:63], v[104:107], v[88:91], v[48:63]
	v_mfma_f32_32x32x16_bf16 v[48:63], v[108:111], v[92:95], v[48:63]
	v_mfma_f32_32x32x16_bf16 v[48:63], v[112:115], v[96:99], v[48:63]
	v_mfma_f32_32x32x16_bf16 v[48:63], v[116:119], v[100:103], v[48:63]
	s_cmp_ge_u32 s19, s18
	s_cbranch_scc1 .Lmla_d3
	s_and_b64 vcc, exec, s[38:39]
	s_cbranch_vccnz .Lmla_d3
	s_add_i32 m0, s7, 0x4000
	s_nop 0
	global_load_lds_dwordx4 v[136:137], off
.Lmla_d3:
	v_add3_u32 v122, s6, v156, v158
	v_add3_u32 v123, s6, v157, v158
	ds_read_b64_tr_b16 v[104:105], v122 offset:12288
	ds_read_b64_tr_b16 v[106:107], v122 offset:13312
	ds_read_b64_tr_b16 v[108:109], v123 offset:12288
	ds_read_b64_tr_b16 v[110:111], v123 offset:13312
	ds_read_b64_tr_b16 v[112:113], v122 offset:14336
	ds_read_b64_tr_b16 v[114:115], v122 offset:15360
	ds_read_b64_tr_b16 v[116:117], v123 offset:14336
	ds_read_b64_tr_b16 v[118:119], v123 offset:15360
	v_max3_f32 v124, v64, v65, v66
	v_max3_f32 v125, v67, v68, v69
	v_max3_f32 v126, v70, v71, v72
	v_max3_f32 v127, v73, v74, v75
	v_max3_f32 v124, v124, v76, v77
	v_max3_f32 v125, v125, v78, v79
	v_max3_f32 v126, v126, v48, v49
	v_max3_f32 v127, v127, v50, v51
	v_max3_f32 v124, v124, v52, v53
	v_max3_f32 v125, v125, v54, v55
	v_max3_f32 v126, v126, v56, v57
	v_max3_f32 v127, v127, v58, v59
	v_max3_f32 v124, v124, v60, v61
	v_max3_f32 v125, v125, v62, v63
	v_max3_f32 v124, v124, v125, v126
	v_max_f32_e32 v124, v124, v127
	v_cmp_lt_f32_e32 vcc, s33, v124
	s_cbranch_vccz .LBB0_170
	v_mov_b32_e32 v121, v124
	s_nop 1
	v_permlane32_swap_b32_e32 v124, v121
	v_max_f32_e32 v124, v124, v121
	v_max_f32_e32 v32, 0, v124
	v_exp_f32_e64 v34, -v32
	v_add_f32_e32 v135, v135, v32
	v_pk_add_f32 v[64:65], v[64:65], v[32:33] op_sel_hi:[1,0] neg_lo:[0,1] neg_hi:[0,1]
	v_pk_add_f32 v[66:67], v[66:67], v[32:33] op_sel_hi:[1,0] neg_lo:[0,1] neg_hi:[0,1]
	v_pk_add_f32 v[68:69], v[68:69], v[32:33] op_sel_hi:[1,0] neg_lo:[0,1] neg_hi:[0,1]
	v_pk_add_f32 v[70:71], v[70:71], v[32:33] op_sel_hi:[1,0] neg_lo:[0,1] neg_hi:[0,1]
	v_pk_add_f32 v[72:73], v[72:73], v[32:33] op_sel_hi:[1,0] neg_lo:[0,1] neg_hi:[0,1]
	v_pk_add_f32 v[74:75], v[74:75], v[32:33] op_sel_hi:[1,0] neg_lo:[0,1] neg_hi:[0,1]
	v_pk_add_f32 v[76:77], v[76:77], v[32:33] op_sel_hi:[1,0] neg_lo:[0,1] neg_hi:[0,1]
	v_pk_add_f32 v[78:79], v[78:79], v[32:33] op_sel_hi:[1,0] neg_lo:[0,1] neg_hi:[0,1]
	v_pk_add_f32 v[48:49], v[48:49], v[32:33] op_sel_hi:[1,0] neg_lo:[0,1] neg_hi:[0,1]
	v_pk_add_f32 v[50:51], v[50:51], v[32:33] op_sel_hi:[1,0] neg_lo:[0,1] neg_hi:[0,1]
	v_pk_add_f32 v[52:53], v[52:53], v[32:33] op_sel_hi:[1,0] neg_lo:[0,1] neg_hi:[0,1]
	v_pk_add_f32 v[54:55], v[54:55], v[32:33] op_sel_hi:[1,0] neg_lo:[0,1] neg_hi:[0,1]
	v_pk_add_f32 v[56:57], v[56:57], v[32:33] op_sel_hi:[1,0] neg_lo:[0,1] neg_hi:[0,1]
	v_pk_add_f32 v[58:59], v[58:59], v[32:33] op_sel_hi:[1,0] neg_lo:[0,1] neg_hi:[0,1]
	v_pk_add_f32 v[60:61], v[60:61], v[32:33] op_sel_hi:[1,0] neg_lo:[0,1] neg_hi:[0,1]
	v_pk_add_f32 v[62:63], v[62:63], v[32:33] op_sel_hi:[1,0] neg_lo:[0,1] neg_hi:[0,1]
	v_xor_b32_e32 v32, 0x80000000, v135
	v_pk_mul_f32 v[14:15], v[14:15], v[34:35] op_sel_hi:[1,0]
	v_pk_mul_f32 v[12:13], v[12:13], v[34:35] op_sel_hi:[1,0]
	v_pk_mul_f32 v[10:11], v[10:11], v[34:35] op_sel_hi:[1,0]
	v_pk_mul_f32 v[8:9], v[8:9], v[34:35] op_sel_hi:[1,0]
	v_pk_mul_f32 v[6:7], v[6:7], v[34:35] op_sel_hi:[1,0]
	v_pk_mul_f32 v[4:5], v[4:5], v[34:35] op_sel_hi:[1,0]
	v_pk_mul_f32 v[2:3], v[2:3], v[34:35] op_sel_hi:[1,0]
	v_pk_mul_f32 v[0:1], v[0:1], v[34:35] op_sel_hi:[1,0]
	v_pk_mul_f32 v[30:31], v[30:31], v[34:35] op_sel_hi:[1,0]
	v_pk_mul_f32 v[28:29], v[28:29], v[34:35] op_sel_hi:[1,0]
	v_pk_mul_f32 v[26:27], v[26:27], v[34:35] op_sel_hi:[1,0]
	v_pk_mul_f32 v[24:25], v[24:25], v[34:35] op_sel_hi:[1,0]
	v_pk_mul_f32 v[22:23], v[22:23], v[34:35] op_sel_hi:[1,0]
	v_pk_mul_f32 v[20:21], v[20:21], v[34:35] op_sel_hi:[1,0]
	v_pk_mul_f32 v[18:19], v[18:19], v[34:35] op_sel_hi:[1,0]
	v_pk_mul_f32 v[16:17], v[16:17], v[34:35] op_sel_hi:[1,0]
	v_mul_f32_e32 v134, v134, v34
	v_mov_b32_e32 v33, v32
	v_mov_b32_e32 v34, v32
	v_mov_b32_e32 v35, v32
	v_mov_b32_e32 v36, v32
	v_mov_b32_e32 v37, v32
	v_mov_b32_e32 v38, v32
	v_mov_b32_e32 v39, v32
	v_mov_b32_e32 v40, v32
	v_mov_b32_e32 v41, v32
	v_mov_b32_e32 v42, v32
	v_mov_b32_e32 v43, v32
	v_mov_b32_e32 v44, v32
	v_mov_b32_e32 v45, v32
	v_mov_b32_e32 v46, v32
	v_mov_b32_e32 v47, v32
	s_branch .LBB0_170
